# MLA units (A12): one static s_setprio 1 for the younger wave half (waves 4-7) at phase entry, back to 0 after the MLA unit loop; no per-segment toggling
# baseline (speedup 1.0000x reference)
; __device__ __forceinline__ void seq_of(int s, int& start, int& len) { if (s < 4) { start = s * SP; len = SP; } else { start = MP + (s - 4) * SS; len = SS; } }
; __global__ void __launch_bounds__(512) mega_fwd(Params P) {
;     ...
;         PHASE_BEGIN
;         {
;             constexpr int N_MLA_L = 768, N_MLA_S = 192, N_A = 2 * 6 * 160, N_S1 = NCHUNK;
;             const int total = N_MLA_L + N_MLA_S + N_A + N_S1;
;             int i = bx;
;             for (; i < N_MLA_L + N_MLA_S; i += G) {
;                 {
;                     int s, h, qb;
;                     if (i < N_MLA_L) { const int b = i & 255, rnd = i >> 8, pair = rnd * 8 + (b & 7); s = pair / 6; h = pair % 6; qb = b >> 3; }
;                     else { const int k = i - N_MLA_L; const int pair = k >> 3; s = 4 + pair / 6; h = pair % 6; qb = k & 7; }
;                     int st, len; seq_of(s, st, len);
;                     att::Desc d{}; d.Q = QB + h * 192; d.ldq = 1280; d.K = KV + h * 256; d.V = KV + h * 256 + 128; d.ldk = 1536; d.KR = KR2; d.O = YB + h * 128; d.ldo = 768;
;                     d.qrow0 = st + qb * 256; d.kvrow0 = st; d.NT = len / 64; const float sc = 0.07216878364870323f; d.C = sc * 1.4426950408889634f; d.THRS = att::THR / sc; d.rope = ROPE; d.pos0 = qb * 256;
;                     __syncthreads(); att::body<1>(d, (char*)lds, wave);
.LBB0_788:
	v_readlane_b32 s38, v253, 0
	s_cmp_ge_i32 s29, s38
	v_readlane_b32 s39, v253, 1
	s_cselect_b64 s[52:53], -1, 0
	s_and_b64 s[38:39], s[52:53], s[76:77]
	s_andn2_b64 vcc, exec, s[38:39]
	v_readlane_b32 s38, v253, 52
	v_readlane_b32 s39, v253, 53
	s_nop 1
	v_cndmask_b32_e64 v0, 0, 1, s[38:39]
	v_cmp_ne_u32_e64 s[42:43], 1, v0
	s_cbranch_vccnz .LBB0_1002
	v_readlane_b32 s58, v253, 2
	v_readlane_b32 s59, v253, 3
	s_load_dwordx2 s[56:57], s[58:59], 0x128
	v_readlane_b32 s29, v253, 6
	s_lshl_b32 s29, s29, 6
	s_cmp_gt_u32 s29, 0xff
	s_cbranch_scc0 .Lmy_prio_skip
	s_setprio 1
.Lmy_prio_skip:
	v_mbcnt_lo_u32_b32 v0, -1, 0
	v_mbcnt_hi_u32_b32 v0, -1, v0
	s_mov_b32 s38, s3
	v_add_u32_e32 v0, s29, v0
	s_and_b64 vcc, exec, s[42:43]
	s_mov_b32 s54, s2
	s_cbranch_vccnz .LBB0_816
	s_waitcnt lgkmcnt(0)
	s_add_u32 s55, s56, 0x1df00000
	s_addc_u32 s64, s57, 0
	s_add_u32 s65, s56, 0x2fc00000
	s_addc_u32 s66, s57, 0
	s_add_u32 s48, s56, 0x3f200000
	s_addc_u32 s49, s57, 0
	s_add_u32 s67, s56, 0x28400000
	s_addc_u32 s68, s57, 0
	s_add_u32 s50, s56, 0x100000
	s_addc_u32 s51, s57, 0
	s_mov_b32 s54, s2
	s_branch .LBB0_792

; __device__ __forceinline__ void seq_of(int s, int& start, int& len) { if (s < 4) { start = s * SP; len = SP; } else { start = MP + (s - 4) * SS; len = SS; } }
; __device__ __forceinline__ void row_seq(int m, int& s, int& t) { if (m < MP) { s = m >> 13; t = m & (SP - 1); } else { const int r = m - MP; s = 4 + (r >> 11); t = r & (SS - 1); } }
; __global__ void __launch_bounds__(512) mega_fwd(Params P) {
;     ...
;             for (; i < N_MLA_L + N_MLA_S + N_A; i += G) {
;                 {
;                     const int k = i - (N_MLA_L + N_MLA_S); const int br = k / 960, k2 = k % 960, h = k2 / 160, rb = k2 % 160;
;                     const int m0g = rb * 256; int s, t; row_seq(m0g, s, t); int st, len; seq_of(s, st, len); const int ui = t >> 8;
;                     const int dil = br ? 4 : 1; const int ncls = len / dil;
;                     att::Desc d{}; d.Q = PA + h * 128; d.K = PA + 768 + h * 128; d.V = PA + 1536 + h * 128; d.ldq = 2304; d.ldk = 2304; d.O = (br ? OA2 : OA1) + h * 128; d.ldo = 768; d.NT = 6;
.LBB0_816:
	s_setprio 0
	s_cmpk_gt_u32 s54, 0xb3f
	s_cbranch_scc1 .LBB0_997
	s_waitcnt lgkmcnt(0)
	s_add_u32 s55, s56, 0x12b00000
	s_addc_u32 s68, s57, 0
	s_add_u32 s69, s56, 0x12b00600
	s_addc_u32 s70, s57, 0
	s_add_u32 s71, s56, 0x12b00c00
	s_addc_u32 s72, s57, 0
	s_branch .LBB0_819
